# GEMM main loops: LDS-DMA loads take the tile base from an SGPR pair plus a 32-bit lane offset (drops 20 per-iteration 64-bit VALU address adds and the VALU-to-VMEM dependency)
# speedup vs baseline: 1.0126x; 1.0056x over previous
; #define PG8_STAGE(bufoff, gbase, voff) do { _Pragma("unroll") for (int _i = 0; _i < 2; ++_i) \
;         __builtin_amdgcn_global_load_lds((const unsigned*)((const char*)(gbase) + (voff)[_i]), (PG8_LAS unsigned*)(lds + (bufoff) + ldsw + _i * 8192), 16, 0, 0); } while (0)
; #define PG8_LDA(dst, b, h) do { _Pragma("unroll") for (int m = 0; m < 4; ++m) _Pragma("unroll") for (int k = 0; k < 2; ++k) dst[m][k] = *(const PG8_LAS bf16x8*)(lds + PG8_SA(b, h) + aoff + m * 2048 + k * 1024); } while (0)
; #define PG8_LDB(dst, b, h) do { _Pragma("unroll") for (int n = 0; n < 2; ++n) _Pragma("unroll") for (int k = 0; k < 2; ++k) dst[n][k] = *(const PG8_LAS bf16x8*)(lds + PG8_SB(b, h) + boff + n * 2048 + k * 1024); } while (0)
; #define PG8_MMA(ai, bj, At, Bt) do { __builtin_amdgcn_s_setprio(1); _Pragma("unroll") for (int m = 0; m < 4; ++m) _Pragma("unroll") for (int n = 0; n < 2; ++n) _Pragma("unroll") for (int k = 0; k < 2; ++k) \
;         acc[ai][bj][m][n] = __builtin_amdgcn_mfma_f32_16x16x32_bf16(Bt[n][k], At[m][k], acc[ai][bj][m][n], 0, 0, 0); __builtin_amdgcn_s_setprio(0); } while (0)
; #define PG8_WAIT_V(n) asm volatile("s_waitcnt vmcnt(" #n ")" ::: "memory")
; #define PG8_WAIT_L(n) asm volatile("s_waitcnt lgkmcnt(" #n ")" ::: "memory")
; #define PG8_BAR __builtin_amdgcn_s_barrier()
; #define PG8_SCHED __builtin_amdgcn_sched_barrier(0)
; template <class Epi, class Sched, bool ALIGN_EPI = false, bool SP2 = false>
; __device__ __forceinline__ void gemm_phase(PG8_LAS unsigned char* lds, const Gemm g, const Sched& S, const Epi& E) {
;     ...
;             PG8_LDB(B0, 0, 0); PG8_LDB(B1, 0, 1); PG8_SCHED; PG8_LDA(At, 0, 0); PG8_STAGE(PG8_SA(1, 1), a1 + hstep, voffA);
;             PG8_WAIT_V(8); PG8_WAIT_L(0); PG8_BAR; PG8_MMA(0, 0, At, B0); PG8_MMA(0, 1, At, B1); PG8_BAR; PG8_SCHED;
;             PG8_LDA(At, 0, 1); PG8_STAGE(PG8_SB(0, 0), b2, voffB); PG8_STAGE(PG8_SB(0, 1), b2 + hstep, voffB); PG8_STAGE(PG8_SA(0, 0), a2, voffA);
.LBB0_436:
	s_add_u32 s16, s14, 0xfff80080
	s_addc_u32 s17, s15, -1
	s_add_i32 s48, 0, 0x10000
	s_cmp_eq_u32 s47, 28
	s_cselect_b32 s19, s9, s17
	s_cselect_b32 s18, s43, s16
	s_cselect_b32 s17, s7, s46
	s_cselect_b32 s16, s44, s45
	s_add_i32 s50, 0, 0x14000
	v_add_u32_e32 v156, s48, v140
	v_add_u32_e32 v172, s50, v140
	ds_read_b128 v[144:147], v156
	ds_read_b128 v[148:151], v156 offset:1024
	ds_read_b128 v[152:155], v156 offset:2048
	ds_read_b128 v[156:159], v156 offset:3072
	ds_read_b128 v[160:163], v172
	ds_read_b128 v[164:167], v172 offset:1024
	ds_read_b128 v[168:171], v172 offset:2048
	ds_read_b128 v[172:175], v172 offset:3072
	s_add_i32 m0, s23, 0xc000
	ds_read_b128 v[176:179], v143
	ds_read_b128 v[180:183], v143 offset:1024
	ds_read_b128 v[184:187], v143 offset:2048
	ds_read_b128 v[188:191], v143 offset:3072
	ds_read_b128 v[192:195], v143 offset:4096
	ds_read_b128 v[196:199], v143 offset:5120
	ds_read_b128 v[200:203], v143 offset:6144
	ds_read_b128 v[204:207], v143 offset:7168
	global_load_lds_dwordx4 v138, s[14:15]
	s_add_i32 m0, s23, 0xe000
	s_nop 0
	global_load_lds_dwordx4 v136, s[14:15]
	s_waitcnt vmcnt(8)
	s_waitcnt lgkmcnt(0)
	s_barrier
	s_setprio 1
	s_waitcnt lgkmcnt(0)
	v_mfma_f32_16x16x32_bf16 v[114:117], v[144:147], v[176:179], v[114:117]
	v_mfma_f32_16x16x32_bf16 v[118:121], v[152:155], v[176:179], v[118:121]
	v_mfma_f32_16x16x32_bf16 v[102:105], v[144:147], v[184:187], v[102:105]
	v_mfma_f32_16x16x32_bf16 v[106:109], v[152:155], v[184:187], v[106:109]
	v_mfma_f32_16x16x32_bf16 v[86:89], v[144:147], v[192:195], v[86:89]
	v_mfma_f32_16x16x32_bf16 v[82:85], v[152:155], v[192:195], v[82:85]
	v_mfma_f32_16x16x32_bf16 v[78:81], v[144:147], v[200:203], v[78:81]
	v_mfma_f32_16x16x32_bf16 v[58:61], v[152:155], v[200:203], v[58:61]
	v_mfma_f32_16x16x32_bf16 v[114:117], v[148:151], v[180:183], v[114:117]
	v_mfma_f32_16x16x32_bf16 v[118:121], v[156:159], v[180:183], v[118:121]
	v_mfma_f32_16x16x32_bf16 v[102:105], v[148:151], v[188:191], v[102:105]
	v_mfma_f32_16x16x32_bf16 v[106:109], v[156:159], v[188:191], v[106:109]
	v_mfma_f32_16x16x32_bf16 v[86:89], v[148:151], v[196:199], v[86:89]
	v_mfma_f32_16x16x32_bf16 v[82:85], v[156:159], v[196:199], v[82:85]
	v_mfma_f32_16x16x32_bf16 v[78:81], v[148:151], v[204:207], v[78:81]
	v_mfma_f32_16x16x32_bf16 v[58:61], v[156:159], v[204:207], v[58:61]
	s_setprio 0
	s_setprio 1
	v_mfma_f32_16x16x32_bf16 v[122:125], v[160:163], v[176:179], v[122:125]
	v_mfma_f32_16x16x32_bf16 v[126:129], v[168:171], v[176:179], v[126:129]
	v_mfma_f32_16x16x32_bf16 v[110:113], v[160:163], v[184:187], v[110:113]
	v_mfma_f32_16x16x32_bf16 v[98:101], v[168:171], v[184:187], v[98:101]
	v_mfma_f32_16x16x32_bf16 v[90:93], v[160:163], v[192:195], v[90:93]
	v_mfma_f32_16x16x32_bf16 v[94:97], v[168:171], v[192:195], v[94:97]
	v_mfma_f32_16x16x32_bf16 v[70:73], v[160:163], v[200:203], v[70:73]
	v_mfma_f32_16x16x32_bf16 v[74:77], v[168:171], v[200:203], v[74:77]
	v_mfma_f32_16x16x32_bf16 v[122:125], v[164:167], v[180:183], v[122:125]
	v_mfma_f32_16x16x32_bf16 v[126:129], v[172:175], v[180:183], v[126:129]
	v_mfma_f32_16x16x32_bf16 v[110:113], v[164:167], v[188:191], v[110:113]
	v_mfma_f32_16x16x32_bf16 v[98:101], v[172:175], v[188:191], v[98:101]
	v_mfma_f32_16x16x32_bf16 v[90:93], v[164:167], v[196:199], v[90:93]
	v_mfma_f32_16x16x32_bf16 v[94:97], v[172:175], v[196:199], v[94:97]
	v_mfma_f32_16x16x32_bf16 v[70:73], v[164:167], v[204:207], v[70:73]
	v_mfma_f32_16x16x32_bf16 v[74:77], v[172:175], v[204:207], v[74:77]
	s_setprio 0
	s_barrier
	s_add_i32 s48, s48, s22
	v_lshl_add_u64 v[208:209], s[16:17], 0, v[0:1]
	s_mov_b32 m0, s48
	ds_read_b128 v[176:179], v143 offset:16384
	ds_read_b128 v[180:183], v143 offset:17408
	ds_read_b128 v[184:187], v143 offset:18432
	ds_read_b128 v[188:191], v143 offset:19456
	ds_read_b128 v[192:195], v143 offset:20480
	ds_read_b128 v[196:199], v143 offset:21504
	ds_read_b128 v[200:203], v143 offset:22528
	ds_read_b128 v[204:207], v143 offset:23552
	global_load_lds_dwordx4 v0, s[16:17]
	s_add_i32 m0, s48, 0x2000
	s_add_u32 s48, s16, 0x80000
	v_lshl_add_u64 v[210:211], s[16:17], 0, v[130:131]
	s_addc_u32 s49, s17, 0
	s_add_i32 s50, s50, s22
	global_load_lds_dwordx4 v130, s[16:17]
	s_mov_b32 m0, s50
	v_lshl_add_u64 v[218:219], s[18:19], 0, v[132:133]
	global_load_lds_dwordx4 v0, s[48:49]
	s_add_i32 m0, s50, 0x2000
	s_nop 0
	global_load_lds_dwordx4 v130, s[48:49]
	v_lshl_add_u64 v[212:213], s[18:19], 0, v[134:135]
	s_mov_b32 m0, s23
	s_nop 0
	global_load_lds_dwordx4 v134, s[18:19]
	s_mov_b32 m0, s24
	s_nop 0
	global_load_lds_dwordx4 v132, s[18:19]
	s_waitcnt vmcnt(8)
	s_waitcnt lgkmcnt(0)
	s_barrier
; #define PG8_STAGE(bufoff, gbase, voff) do { _Pragma("unroll") for (int _i = 0; _i < 2; ++_i) \
;         __builtin_amdgcn_global_load_lds((const unsigned*)((const char*)(gbase) + (voff)[_i]), (PG8_LAS unsigned*)(lds + (bufoff) + ldsw + _i * 8192), 16, 0, 0); } while (0)
; #define PG8_LDA(dst, b, h) do { _Pragma("unroll") for (int m = 0; m < 4; ++m) _Pragma("unroll") for (int k = 0; k < 2; ++k) dst[m][k] = *(const PG8_LAS bf16x8*)(lds + PG8_SA(b, h) + aoff + m * 2048 + k * 1024); } while (0)
; #define PG8_LDB(dst, b, h) do { _Pragma("unroll") for (int n = 0; n < 2; ++n) _Pragma("unroll") for (int k = 0; k < 2; ++k) dst[n][k] = *(const PG8_LAS bf16x8*)(lds + PG8_SB(b, h) + boff + n * 2048 + k * 1024); } while (0)
; #define PG8_MMA(ai, bj, At, Bt) do { __builtin_amdgcn_s_setprio(1); _Pragma("unroll") for (int m = 0; m < 4; ++m) _Pragma("unroll") for (int n = 0; n < 2; ++n) _Pragma("unroll") for (int k = 0; k < 2; ++k) \
;         acc[ai][bj][m][n] = __builtin_amdgcn_mfma_f32_16x16x32_bf16(Bt[n][k], At[m][k], acc[ai][bj][m][n], 0, 0, 0); __builtin_amdgcn_s_setprio(0); } while (0)
; #define PG8_WAIT_V(n) asm volatile("s_waitcnt vmcnt(" #n ")" ::: "memory")
; #define PG8_WAIT_L(n) asm volatile("s_waitcnt lgkmcnt(" #n ")" ::: "memory")
; #define PG8_BAR __builtin_amdgcn_s_barrier()
; #define PG8_SCHED __builtin_amdgcn_sched_barrier(0)
; template <class Epi, class Sched, bool ALIGN_EPI = false, bool SP2 = false>
; __device__ __forceinline__ void gemm_phase(PG8_LAS unsigned char* lds, const Gemm g, const Sched& S, const Epi& E) {
;     ...
;             PG8_WAIT_V(8); PG8_WAIT_L(0); PG8_BAR; PG8_MMA(1, 0, At, B0); PG8_MMA(1, 1, At, B1); PG8_BAR; PG8_SCHED;
;             PG8_LDB(B0, 1, 0); PG8_LDB(B1, 1, 1); PG8_SCHED; PG8_LDA(At, 1, 0); PG8_STAGE(PG8_SA(0, 1), a2 + hstep, voffA);
;             PG8_WAIT_V(8); PG8_WAIT_L(0); PG8_BAR; PG8_MMA(0, 0, At, B0); PG8_MMA(0, 1, At, B1); PG8_BAR; PG8_SCHED;
	s_setprio 1
	s_waitcnt lgkmcnt(0)
	v_mfma_f32_16x16x32_bf16 v[50:53], v[144:147], v[176:179], v[50:53]
	v_mfma_f32_16x16x32_bf16 v[54:57], v[152:155], v[176:179], v[54:57]
	v_mfma_f32_16x16x32_bf16 v[34:37], v[144:147], v[184:187], v[34:37]
	v_mfma_f32_16x16x32_bf16 v[38:41], v[152:155], v[184:187], v[38:41]
	v_mfma_f32_16x16x32_bf16 v[18:21], v[144:147], v[192:195], v[18:21]
	v_mfma_f32_16x16x32_bf16 v[22:25], v[152:155], v[192:195], v[22:25]
	v_mfma_f32_16x16x32_bf16 v[2:5], v[144:147], v[200:203], v[2:5]
	v_mfma_f32_16x16x32_bf16 v[6:9], v[152:155], v[200:203], v[6:9]
	v_mfma_f32_16x16x32_bf16 v[50:53], v[148:151], v[180:183], v[50:53]
	v_mfma_f32_16x16x32_bf16 v[54:57], v[156:159], v[180:183], v[54:57]
	v_mfma_f32_16x16x32_bf16 v[34:37], v[148:151], v[188:191], v[34:37]
	v_mfma_f32_16x16x32_bf16 v[38:41], v[156:159], v[188:191], v[38:41]
	v_mfma_f32_16x16x32_bf16 v[18:21], v[148:151], v[196:199], v[18:21]
	v_mfma_f32_16x16x32_bf16 v[22:25], v[156:159], v[196:199], v[22:25]
	v_mfma_f32_16x16x32_bf16 v[2:5], v[148:151], v[204:207], v[2:5]
	v_mfma_f32_16x16x32_bf16 v[6:9], v[156:159], v[204:207], v[6:9]
	s_setprio 0
	s_setprio 1
	v_mfma_f32_16x16x32_bf16 v[62:65], v[160:163], v[176:179], v[62:65]
	v_mfma_f32_16x16x32_bf16 v[66:69], v[168:171], v[176:179], v[66:69]
	v_mfma_f32_16x16x32_bf16 v[42:45], v[160:163], v[184:187], v[42:45]
	v_mfma_f32_16x16x32_bf16 v[46:49], v[168:171], v[184:187], v[46:49]
	v_mfma_f32_16x16x32_bf16 v[26:29], v[160:163], v[192:195], v[26:29]
	v_mfma_f32_16x16x32_bf16 v[30:33], v[168:171], v[192:195], v[30:33]
	v_mfma_f32_16x16x32_bf16 v[10:13], v[160:163], v[200:203], v[10:13]
	v_mfma_f32_16x16x32_bf16 v[14:17], v[168:171], v[200:203], v[14:17]
	v_mfma_f32_16x16x32_bf16 v[62:65], v[164:167], v[180:183], v[62:65]
	v_mfma_f32_16x16x32_bf16 v[66:69], v[172:175], v[180:183], v[66:69]
	v_mfma_f32_16x16x32_bf16 v[42:45], v[164:167], v[188:191], v[42:45]
	v_mfma_f32_16x16x32_bf16 v[46:49], v[172:175], v[188:191], v[46:49]
	v_mfma_f32_16x16x32_bf16 v[26:29], v[164:167], v[196:199], v[26:29]
	v_mfma_f32_16x16x32_bf16 v[30:33], v[172:175], v[196:199], v[30:33]
	v_mfma_f32_16x16x32_bf16 v[10:13], v[164:167], v[204:207], v[10:13]
	v_mfma_f32_16x16x32_bf16 v[14:17], v[172:175], v[204:207], v[14:17]
	s_setprio 0
	s_barrier
	s_add_i32 s48, 0, 0x18000
	s_add_i32 s49, 0, 0x1c000
	v_add_u32_e32 v156, s48, v140
	v_add_u32_e32 v172, s49, v140
	ds_read_b128 v[144:147], v156
	ds_read_b128 v[148:151], v156 offset:1024
	ds_read_b128 v[152:155], v156 offset:2048
	ds_read_b128 v[156:159], v156 offset:3072
	ds_read_b128 v[160:163], v172
	ds_read_b128 v[164:167], v172 offset:1024
	ds_read_b128 v[168:171], v172 offset:2048
	ds_read_b128 v[172:175], v172 offset:3072
	s_add_u32 s18, s18, 0x80000
	s_addc_u32 s19, s19, 0
	s_mov_b32 m0, s25
	ds_read_b128 v[176:179], v143 offset:32768
	ds_read_b128 v[180:183], v143 offset:33792
	ds_read_b128 v[184:187], v143 offset:34816
	ds_read_b128 v[188:191], v143 offset:35840
	ds_read_b128 v[192:195], v143 offset:36864
	ds_read_b128 v[196:199], v143 offset:37888
	ds_read_b128 v[200:203], v143 offset:38912
	ds_read_b128 v[204:207], v143 offset:39936
	global_load_lds_dwordx4 v134, s[18:19]
	s_mov_b32 m0, s26
	s_nop 0
	global_load_lds_dwordx4 v132, s[18:19]
	s_waitcnt vmcnt(8)
	s_waitcnt lgkmcnt(0)
	s_barrier
	s_setprio 1
	s_waitcnt lgkmcnt(0)
	v_mfma_f32_16x16x32_bf16 v[114:117], v[144:147], v[176:179], v[114:117]
	v_mfma_f32_16x16x32_bf16 v[118:121], v[152:155], v[176:179], v[118:121]
	v_mfma_f32_16x16x32_bf16 v[102:105], v[144:147], v[184:187], v[102:105]
	v_mfma_f32_16x16x32_bf16 v[106:109], v[152:155], v[184:187], v[106:109]
	v_mfma_f32_16x16x32_bf16 v[86:89], v[144:147], v[192:195], v[86:89]
	v_mfma_f32_16x16x32_bf16 v[82:85], v[152:155], v[192:195], v[82:85]
	v_mfma_f32_16x16x32_bf16 v[78:81], v[144:147], v[200:203], v[78:81]
	v_mfma_f32_16x16x32_bf16 v[58:61], v[152:155], v[200:203], v[58:61]
	v_mfma_f32_16x16x32_bf16 v[114:117], v[148:151], v[180:183], v[114:117]
	v_mfma_f32_16x16x32_bf16 v[118:121], v[156:159], v[180:183], v[118:121]
	v_mfma_f32_16x16x32_bf16 v[102:105], v[148:151], v[188:191], v[102:105]
	v_mfma_f32_16x16x32_bf16 v[106:109], v[156:159], v[188:191], v[106:109]
	v_mfma_f32_16x16x32_bf16 v[86:89], v[148:151], v[196:199], v[86:89]
	v_mfma_f32_16x16x32_bf16 v[82:85], v[156:159], v[196:199], v[82:85]
	v_mfma_f32_16x16x32_bf16 v[78:81], v[148:151], v[204:207], v[78:81]
	v_mfma_f32_16x16x32_bf16 v[58:61], v[156:159], v[204:207], v[58:61]
	s_setprio 0
	s_setprio 1
	v_mfma_f32_16x16x32_bf16 v[122:125], v[160:163], v[176:179], v[122:125]
	v_mfma_f32_16x16x32_bf16 v[126:129], v[168:171], v[176:179], v[126:129]
	v_mfma_f32_16x16x32_bf16 v[110:113], v[160:163], v[184:187], v[110:113]
	v_mfma_f32_16x16x32_bf16 v[98:101], v[168:171], v[184:187], v[98:101]
	v_mfma_f32_16x16x32_bf16 v[90:93], v[160:163], v[192:195], v[90:93]
	v_mfma_f32_16x16x32_bf16 v[94:97], v[168:171], v[192:195], v[94:97]
	v_mfma_f32_16x16x32_bf16 v[70:73], v[160:163], v[200:203], v[70:73]
	v_mfma_f32_16x16x32_bf16 v[74:77], v[168:171], v[200:203], v[74:77]
	v_mfma_f32_16x16x32_bf16 v[122:125], v[164:167], v[180:183], v[122:125]
	v_mfma_f32_16x16x32_bf16 v[126:129], v[172:175], v[180:183], v[126:129]
	v_mfma_f32_16x16x32_bf16 v[110:113], v[164:167], v[188:191], v[110:113]
	v_mfma_f32_16x16x32_bf16 v[98:101], v[172:175], v[188:191], v[98:101]
	v_mfma_f32_16x16x32_bf16 v[90:93], v[164:167], v[196:199], v[90:93]
	v_mfma_f32_16x16x32_bf16 v[94:97], v[172:175], v[196:199], v[94:97]
	v_mfma_f32_16x16x32_bf16 v[70:73], v[164:167], v[204:207], v[70:73]
	v_mfma_f32_16x16x32_bf16 v[74:77], v[172:175], v[204:207], v[74:77]
	s_setprio 0
	s_barrier
; #define PG8_STAGE(bufoff, gbase, voff) do { _Pragma("unroll") for (int _i = 0; _i < 2; ++_i) \
;         __builtin_amdgcn_global_load_lds((const unsigned*)((const char*)(gbase) + (voff)[_i]), (PG8_LAS unsigned*)(lds + (bufoff) + ldsw + _i * 8192), 16, 0, 0); } while (0)
; #define PG8_LDA(dst, b, h) do { _Pragma("unroll") for (int m = 0; m < 4; ++m) _Pragma("unroll") for (int k = 0; k < 2; ++k) dst[m][k] = *(const PG8_LAS bf16x8*)(lds + PG8_SA(b, h) + aoff + m * 2048 + k * 1024); } while (0)
; #define PG8_MMA(ai, bj, At, Bt) do { __builtin_amdgcn_s_setprio(1); _Pragma("unroll") for (int m = 0; m < 4; ++m) _Pragma("unroll") for (int n = 0; n < 2; ++n) _Pragma("unroll") for (int k = 0; k < 2; ++k) \
;         acc[ai][bj][m][n] = __builtin_amdgcn_mfma_f32_16x16x32_bf16(Bt[n][k], At[m][k], acc[ai][bj][m][n], 0, 0, 0); __builtin_amdgcn_s_setprio(0); } while (0)
; #define PG8_WAIT_V(n) asm volatile("s_waitcnt vmcnt(" #n ")" ::: "memory")
; #define PG8_WAIT_L(n) asm volatile("s_waitcnt lgkmcnt(" #n ")" ::: "memory")
; #define PG8_BAR __builtin_amdgcn_s_barrier()
; #define PG8_SCHED __builtin_amdgcn_sched_barrier(0)
; template <class Epi, class Sched, bool ALIGN_EPI = false, bool SP2 = false>
; __device__ __forceinline__ void gemm_phase(PG8_LAS unsigned char* lds, const Gemm g, const Sched& S, const Epi& E) {
;     ...
;             PG8_LDA(At, 1, 1); PG8_STAGE(PG8_SB(1, 0), b3, voffB); PG8_STAGE(PG8_SB(1, 1), b3 + hstep, voffB); PG8_STAGE(PG8_SA(1, 0), a3, voffA);
;             PG8_WAIT_V(8); PG8_WAIT_L(0); PG8_BAR; PG8_MMA(1, 0, At, B0); PG8_MMA(1, 1, At, B1); PG8_BAR; PG8_SCHED;
	s_add_i32 s18, s48, s22
	v_lshl_add_u64 v[208:209], v[208:209], 0, s[78:79]
	s_mov_b32 m0, s18
	ds_read_b128 v[176:179], v143 offset:49152
	ds_read_b128 v[180:183], v143 offset:50176
	ds_read_b128 v[184:187], v143 offset:51200
	ds_read_b128 v[188:191], v143 offset:52224
	ds_read_b128 v[192:195], v143 offset:53248
	ds_read_b128 v[196:199], v143 offset:54272
	ds_read_b128 v[200:203], v143 offset:55296
	ds_read_b128 v[204:207], v143 offset:56320
	global_load_lds_dwordx4 v[208:209], off
	s_add_i32 m0, s18, 0x2000
	s_add_u32 s16, s16, 0x80080
	v_lshl_add_u64 v[208:209], v[210:211], 0, s[78:79]
	s_addc_u32 s17, s17, 0
	s_add_i32 s18, s49, s22
	global_load_lds_dwordx4 v[208:209], off
	s_mov_b32 m0, s18
	s_nop 0
	global_load_lds_dwordx4 v0, s[16:17]
	s_add_i32 m0, s18, 0x2000
	s_nop 0
	global_load_lds_dwordx4 v130, s[16:17]
	v_lshl_add_u64 v[208:209], v[212:213], 0, s[78:79]
	s_mov_b32 m0, s27
	s_nop 0
	global_load_lds_dwordx4 v[208:209], off
	v_lshl_add_u64 v[208:209], v[218:219], 0, s[78:79]
	s_mov_b32 m0, s28
	s_nop 0
	global_load_lds_dwordx4 v[208:209], off
	s_waitcnt vmcnt(8)
	s_waitcnt lgkmcnt(0)
	s_barrier
	s_setprio 1
	s_waitcnt lgkmcnt(0)
	v_mfma_f32_16x16x32_bf16 v[50:53], v[144:147], v[176:179], v[50:53]
	v_mfma_f32_16x16x32_bf16 v[54:57], v[152:155], v[176:179], v[54:57]
	v_mfma_f32_16x16x32_bf16 v[34:37], v[144:147], v[184:187], v[34:37]
	v_mfma_f32_16x16x32_bf16 v[38:41], v[152:155], v[184:187], v[38:41]
	v_mfma_f32_16x16x32_bf16 v[18:21], v[144:147], v[192:195], v[18:21]
	v_mfma_f32_16x16x32_bf16 v[22:25], v[152:155], v[192:195], v[22:25]
	v_mfma_f32_16x16x32_bf16 v[2:5], v[144:147], v[200:203], v[2:5]
	v_mfma_f32_16x16x32_bf16 v[6:9], v[152:155], v[200:203], v[6:9]
	v_mfma_f32_16x16x32_bf16 v[50:53], v[148:151], v[180:183], v[50:53]
	v_mfma_f32_16x16x32_bf16 v[54:57], v[156:159], v[180:183], v[54:57]
	v_mfma_f32_16x16x32_bf16 v[34:37], v[148:151], v[188:191], v[34:37]
	v_mfma_f32_16x16x32_bf16 v[38:41], v[156:159], v[188:191], v[38:41]
	v_mfma_f32_16x16x32_bf16 v[18:21], v[148:151], v[196:199], v[18:21]
	v_mfma_f32_16x16x32_bf16 v[22:25], v[156:159], v[196:199], v[22:25]
	v_mfma_f32_16x16x32_bf16 v[2:5], v[148:151], v[204:207], v[2:5]
	v_mfma_f32_16x16x32_bf16 v[6:9], v[156:159], v[204:207], v[6:9]
	s_setprio 0
	s_setprio 1
	v_mfma_f32_16x16x32_bf16 v[62:65], v[160:163], v[176:179], v[62:65]
	v_mfma_f32_16x16x32_bf16 v[66:69], v[168:171], v[176:179], v[66:69]
	v_mfma_f32_16x16x32_bf16 v[42:45], v[160:163], v[184:187], v[42:45]
	v_mfma_f32_16x16x32_bf16 v[46:49], v[168:171], v[184:187], v[46:49]
	v_mfma_f32_16x16x32_bf16 v[26:29], v[160:163], v[192:195], v[26:29]
	v_mfma_f32_16x16x32_bf16 v[30:33], v[168:171], v[192:195], v[30:33]
	v_mfma_f32_16x16x32_bf16 v[10:13], v[160:163], v[200:203], v[10:13]
	v_mfma_f32_16x16x32_bf16 v[14:17], v[168:171], v[200:203], v[14:17]
	v_mfma_f32_16x16x32_bf16 v[62:65], v[164:167], v[180:183], v[62:65]
	v_mfma_f32_16x16x32_bf16 v[66:69], v[172:175], v[180:183], v[66:69]
	v_mfma_f32_16x16x32_bf16 v[42:45], v[164:167], v[188:191], v[42:45]
	v_mfma_f32_16x16x32_bf16 v[46:49], v[172:175], v[188:191], v[46:49]
	v_mfma_f32_16x16x32_bf16 v[26:29], v[164:167], v[196:199], v[26:29]
	v_mfma_f32_16x16x32_bf16 v[30:33], v[172:175], v[196:199], v[30:33]
	v_mfma_f32_16x16x32_bf16 v[10:13], v[164:167], v[204:207], v[10:13]
	v_mfma_f32_16x16x32_bf16 v[14:17], v[172:175], v[204:207], v[14:17]
	s_setprio 0
	s_barrier
	s_add_i32 s47, s47, 2
	s_add_u32 s45, s45, 0x100
	s_addc_u32 s46, s46, 0
	s_add_u32 s14, s14, 0x100
	s_addc_u32 s15, s15, 0
	s_cmp_gt_u32 s47, 29
	s_cbranch_scc0 .LBB0_436
	s_and_b64 vcc, exec, s[4:5]
	v_readlane_b32 s47, v254, 33
	s_cbranch_vccz .LBB0_439
	s_barrier

; #define PG8_STAGE(bufoff, gbase, voff) do { _Pragma("unroll") for (int _i = 0; _i < 2; ++_i) \
;         __builtin_amdgcn_global_load_lds((const unsigned*)((const char*)(gbase) + (voff)[_i]), (PG8_LAS unsigned*)(lds + (bufoff) + ldsw + _i * 8192), 16, 0, 0); } while (0)
; #define PG8_LDA(dst, b, h) do { _Pragma("unroll") for (int m = 0; m < 4; ++m) _Pragma("unroll") for (int k = 0; k < 2; ++k) dst[m][k] = *(const PG8_LAS bf16x8*)(lds + PG8_SA(b, h) + aoff + m * 2048 + k * 1024); } while (0)
; #define PG8_LDB(dst, b, h) do { _Pragma("unroll") for (int n = 0; n < 2; ++n) _Pragma("unroll") for (int k = 0; k < 2; ++k) dst[n][k] = *(const PG8_LAS bf16x8*)(lds + PG8_SB(b, h) + boff + n * 2048 + k * 1024); } while (0)
; #define PG8_MMA(ai, bj, At, Bt) do { __builtin_amdgcn_s_setprio(1); _Pragma("unroll") for (int m = 0; m < 4; ++m) _Pragma("unroll") for (int n = 0; n < 2; ++n) _Pragma("unroll") for (int k = 0; k < 2; ++k) \
;         acc[ai][bj][m][n] = __builtin_amdgcn_mfma_f32_16x16x32_bf16(Bt[n][k], At[m][k], acc[ai][bj][m][n], 0, 0, 0); __builtin_amdgcn_s_setprio(0); } while (0)
; #define PG8_WAIT_V(n) asm volatile("s_waitcnt vmcnt(" #n ")" ::: "memory")
; #define PG8_WAIT_L(n) asm volatile("s_waitcnt lgkmcnt(" #n ")" ::: "memory")
; #define PG8_BAR __builtin_amdgcn_s_barrier()
; #define PG8_SCHED __builtin_amdgcn_sched_barrier(0)
; template <class Epi, class Sched, bool ALIGN_EPI = false, bool SP2 = false>
; __device__ __forceinline__ void gemm_phase(PG8_LAS unsigned char* lds, const Gemm g, const Sched& S, const Epi& E) {
;     ...
;             PG8_LDB(B0, 0, 0); PG8_LDB(B1, 0, 1); PG8_SCHED; PG8_LDA(At, 0, 0); PG8_STAGE(PG8_SA(1, 1), a1 + hstep, voffA);
;             PG8_WAIT_V(8); PG8_WAIT_L(0); PG8_BAR; PG8_MMA(0, 0, At, B0); PG8_MMA(0, 1, At, B1); PG8_BAR; PG8_SCHED;
;             PG8_LDA(At, 0, 1); PG8_STAGE(PG8_SB(0, 0), b2, voffB); PG8_STAGE(PG8_SB(0, 1), b2 + hstep, voffB); PG8_STAGE(PG8_SA(0, 0), a2, voffA);
.LBB0_458:
	s_add_i32 s51, s14, 2
	s_add_u32 s52, s12, 0x80
	s_addc_u32 s15, s13, 0
	s_add_i32 s54, 0, 0x10000
	s_cmp_eq_u32 s36, s14
	s_cselect_b32 s15, s9, s15
	s_cselect_b32 s14, s8, s52
	s_cselect_b32 s53, s11, s45
	s_cselect_b32 s52, s10, s44
	s_add_i32 s55, 0, 0x14000
	v_add_u32_e32 v142, s54, v159
	v_add_u32_e32 v170, s55, v159
	ds_read_b128 v[130:133], v142
	ds_read_b128 v[134:137], v142 offset:1024
	ds_read_b128 v[138:141], v142 offset:2048
	ds_read_b128 v[142:145], v142 offset:3072
	ds_read_b128 v[146:149], v170
	ds_read_b128 v[150:153], v170 offset:1024
	ds_read_b128 v[154:157], v170 offset:2048
	ds_read_b128 v[170:173], v170 offset:3072
	s_add_i32 m0, s20, 0xc000
	ds_read_b128 v[174:177], v188
	ds_read_b128 v[178:181], v188 offset:1024
	ds_read_b128 v[182:185], v188 offset:2048
	ds_read_b128 v[190:193], v188 offset:3072
	ds_read_b128 v[194:197], v188 offset:4096
	ds_read_b128 v[198:201], v188 offset:5120
	ds_read_b128 v[202:205], v188 offset:6144
	ds_read_b128 v[206:209], v188 offset:7168
	global_load_lds_dwordx4 v168, s[12:13]
	s_add_i32 m0, s20, 0xe000
	s_nop 0
	global_load_lds_dwordx4 v166, s[12:13]
	s_waitcnt vmcnt(8)
	s_waitcnt lgkmcnt(0)
	s_barrier
	s_setprio 1
	s_waitcnt lgkmcnt(0)
	v_mfma_f32_16x16x32_bf16 v[126:129], v[130:133], v[174:177], v[126:129]
	v_mfma_f32_16x16x32_bf16 v[122:125], v[138:141], v[174:177], v[122:125]
	v_mfma_f32_16x16x32_bf16 v[110:113], v[130:133], v[182:185], v[110:113]
	v_mfma_f32_16x16x32_bf16 v[106:109], v[138:141], v[182:185], v[106:109]
	v_mfma_f32_16x16x32_bf16 v[94:97], v[130:133], v[194:197], v[94:97]
	v_mfma_f32_16x16x32_bf16 v[90:93], v[138:141], v[194:197], v[90:93]
	v_mfma_f32_16x16x32_bf16 v[78:81], v[130:133], v[202:205], v[78:81]
	v_mfma_f32_16x16x32_bf16 v[74:77], v[138:141], v[202:205], v[74:77]
	v_mfma_f32_16x16x32_bf16 v[126:129], v[134:137], v[178:181], v[126:129]
	v_mfma_f32_16x16x32_bf16 v[122:125], v[142:145], v[178:181], v[122:125]
	v_mfma_f32_16x16x32_bf16 v[110:113], v[134:137], v[190:193], v[110:113]
	v_mfma_f32_16x16x32_bf16 v[106:109], v[142:145], v[190:193], v[106:109]
	v_mfma_f32_16x16x32_bf16 v[94:97], v[134:137], v[198:201], v[94:97]
	v_mfma_f32_16x16x32_bf16 v[90:93], v[142:145], v[198:201], v[90:93]
	v_mfma_f32_16x16x32_bf16 v[78:81], v[134:137], v[206:209], v[78:81]
	v_mfma_f32_16x16x32_bf16 v[74:77], v[142:145], v[206:209], v[74:77]
	s_setprio 0
	s_setprio 1
	v_mfma_f32_16x16x32_bf16 v[118:121], v[146:149], v[174:177], v[118:121]
	v_mfma_f32_16x16x32_bf16 v[114:117], v[154:157], v[174:177], v[114:117]
	v_mfma_f32_16x16x32_bf16 v[102:105], v[146:149], v[182:185], v[102:105]
	v_mfma_f32_16x16x32_bf16 v[98:101], v[154:157], v[182:185], v[98:101]
	v_mfma_f32_16x16x32_bf16 v[86:89], v[146:149], v[194:197], v[86:89]
	v_mfma_f32_16x16x32_bf16 v[82:85], v[154:157], v[194:197], v[82:85]
	v_mfma_f32_16x16x32_bf16 v[70:73], v[146:149], v[202:205], v[70:73]
	v_mfma_f32_16x16x32_bf16 v[66:69], v[154:157], v[202:205], v[66:69]
	v_mfma_f32_16x16x32_bf16 v[118:121], v[150:153], v[178:181], v[118:121]
	v_mfma_f32_16x16x32_bf16 v[114:117], v[170:173], v[178:181], v[114:117]
	v_mfma_f32_16x16x32_bf16 v[102:105], v[150:153], v[190:193], v[102:105]
	v_mfma_f32_16x16x32_bf16 v[98:101], v[170:173], v[190:193], v[98:101]
	v_mfma_f32_16x16x32_bf16 v[86:89], v[150:153], v[198:201], v[86:89]
	v_mfma_f32_16x16x32_bf16 v[82:85], v[170:173], v[198:201], v[82:85]
	v_mfma_f32_16x16x32_bf16 v[70:73], v[150:153], v[206:209], v[70:73]
	v_mfma_f32_16x16x32_bf16 v[66:69], v[170:173], v[206:209], v[66:69]
	s_setprio 0
	s_barrier
	s_add_i32 s54, s54, s19
	v_lshl_add_u64 v[210:211], s[52:53], 0, v[0:1]
	s_mov_b32 m0, s54
	ds_read_b128 v[174:177], v188 offset:16384
	ds_read_b128 v[178:181], v188 offset:17408
	ds_read_b128 v[182:185], v188 offset:18432
	ds_read_b128 v[190:193], v188 offset:19456
	ds_read_b128 v[194:197], v188 offset:20480
	ds_read_b128 v[198:201], v188 offset:21504
	ds_read_b128 v[202:205], v188 offset:22528
	ds_read_b128 v[206:209], v188 offset:23552
	global_load_lds_dwordx4 v0, s[52:53]
	s_add_i32 m0, s54, 0x2000
	v_lshl_add_u64 v[212:213], s[52:53], 0, v[160:161]
	s_add_u32 s52, s52, s86
	s_addc_u32 s53, s53, 0
	s_add_i32 s54, s55, s19
	global_load_lds_dwordx4 v[212:213], off
	v_lshl_add_u64 v[218:219], s[52:53], 0, v[0:1]
	s_mov_b32 m0, s54
	v_lshl_add_u64 v[220:221], s[52:53], 0, v[160:161]
	global_load_lds_dwordx4 v0, s[52:53]
	s_add_i32 m0, s54, 0x2000
	v_lshl_add_u64 v[222:223], s[14:15], 0, v[162:163]
	global_load_lds_dwordx4 v160, s[52:53]
	s_mov_b32 m0, s20
	v_lshl_add_u64 v[224:225], s[14:15], 0, v[164:165]
	global_load_lds_dwordx4 v162, s[14:15]
	s_mov_b32 m0, s21
	s_nop 0
	global_load_lds_dwordx4 v164, s[14:15]
	s_waitcnt vmcnt(8)
	s_waitcnt lgkmcnt(0)
	s_barrier
; #define PG8_STAGE(bufoff, gbase, voff) do { _Pragma("unroll") for (int _i = 0; _i < 2; ++_i) \
;         __builtin_amdgcn_global_load_lds((const unsigned*)((const char*)(gbase) + (voff)[_i]), (PG8_LAS unsigned*)(lds + (bufoff) + ldsw + _i * 8192), 16, 0, 0); } while (0)
; #define PG8_LDA(dst, b, h) do { _Pragma("unroll") for (int m = 0; m < 4; ++m) _Pragma("unroll") for (int k = 0; k < 2; ++k) dst[m][k] = *(const PG8_LAS bf16x8*)(lds + PG8_SA(b, h) + aoff + m * 2048 + k * 1024); } while (0)
; #define PG8_LDB(dst, b, h) do { _Pragma("unroll") for (int n = 0; n < 2; ++n) _Pragma("unroll") for (int k = 0; k < 2; ++k) dst[n][k] = *(const PG8_LAS bf16x8*)(lds + PG8_SB(b, h) + boff + n * 2048 + k * 1024); } while (0)
; #define PG8_MMA(ai, bj, At, Bt) do { __builtin_amdgcn_s_setprio(1); _Pragma("unroll") for (int m = 0; m < 4; ++m) _Pragma("unroll") for (int n = 0; n < 2; ++n) _Pragma("unroll") for (int k = 0; k < 2; ++k) \
;         acc[ai][bj][m][n] = __builtin_amdgcn_mfma_f32_16x16x32_bf16(Bt[n][k], At[m][k], acc[ai][bj][m][n], 0, 0, 0); __builtin_amdgcn_s_setprio(0); } while (0)
; #define PG8_WAIT_V(n) asm volatile("s_waitcnt vmcnt(" #n ")" ::: "memory")
; #define PG8_WAIT_L(n) asm volatile("s_waitcnt lgkmcnt(" #n ")" ::: "memory")
; #define PG8_BAR __builtin_amdgcn_s_barrier()
; #define PG8_SCHED __builtin_amdgcn_sched_barrier(0)
; template <class Epi, class Sched, bool ALIGN_EPI = false, bool SP2 = false>
; __device__ __forceinline__ void gemm_phase(PG8_LAS unsigned char* lds, const Gemm g, const Sched& S, const Epi& E) {
;     ...
;             PG8_WAIT_V(8); PG8_WAIT_L(0); PG8_BAR; PG8_MMA(1, 0, At, B0); PG8_MMA(1, 1, At, B1); PG8_BAR; PG8_SCHED;
;             PG8_LDB(B0, 1, 0); PG8_LDB(B1, 1, 1); PG8_SCHED; PG8_LDA(At, 1, 0); PG8_STAGE(PG8_SA(0, 1), a2 + hstep, voffA);
;             PG8_WAIT_V(8); PG8_WAIT_L(0); PG8_BAR; PG8_MMA(0, 0, At, B0); PG8_MMA(0, 1, At, B1); PG8_BAR; PG8_SCHED;
	s_setprio 1
	s_waitcnt lgkmcnt(0)
	v_mfma_f32_16x16x32_bf16 v[62:65], v[130:133], v[174:177], v[62:65]
	v_mfma_f32_16x16x32_bf16 v[58:61], v[138:141], v[174:177], v[58:61]
	v_mfma_f32_16x16x32_bf16 v[42:45], v[130:133], v[182:185], v[42:45]
	v_mfma_f32_16x16x32_bf16 v[38:41], v[138:141], v[182:185], v[38:41]
	v_mfma_f32_16x16x32_bf16 v[22:25], v[130:133], v[194:197], v[22:25]
	v_mfma_f32_16x16x32_bf16 v[18:21], v[138:141], v[194:197], v[18:21]
	v_mfma_f32_16x16x32_bf16 v[6:9], v[130:133], v[202:205], v[6:9]
	v_mfma_f32_16x16x32_bf16 v[2:5], v[138:141], v[202:205], v[2:5]
	v_mfma_f32_16x16x32_bf16 v[62:65], v[134:137], v[178:181], v[62:65]
	v_mfma_f32_16x16x32_bf16 v[58:61], v[142:145], v[178:181], v[58:61]
	v_mfma_f32_16x16x32_bf16 v[42:45], v[134:137], v[190:193], v[42:45]
	v_mfma_f32_16x16x32_bf16 v[38:41], v[142:145], v[190:193], v[38:41]
	v_mfma_f32_16x16x32_bf16 v[22:25], v[134:137], v[198:201], v[22:25]
	v_mfma_f32_16x16x32_bf16 v[18:21], v[142:145], v[198:201], v[18:21]
	v_mfma_f32_16x16x32_bf16 v[6:9], v[134:137], v[206:209], v[6:9]
	v_mfma_f32_16x16x32_bf16 v[2:5], v[142:145], v[206:209], v[2:5]
	s_setprio 0
	s_setprio 1
	v_mfma_f32_16x16x32_bf16 v[54:57], v[146:149], v[174:177], v[54:57]
	v_mfma_f32_16x16x32_bf16 v[50:53], v[154:157], v[174:177], v[50:53]
	v_mfma_f32_16x16x32_bf16 v[34:37], v[146:149], v[182:185], v[34:37]
	v_mfma_f32_16x16x32_bf16 v[46:49], v[154:157], v[182:185], v[46:49]
	v_mfma_f32_16x16x32_bf16 v[30:33], v[146:149], v[194:197], v[30:33]
	v_mfma_f32_16x16x32_bf16 v[26:29], v[154:157], v[194:197], v[26:29]
	v_mfma_f32_16x16x32_bf16 v[14:17], v[146:149], v[202:205], v[14:17]
	v_mfma_f32_16x16x32_bf16 v[10:13], v[154:157], v[202:205], v[10:13]
	v_mfma_f32_16x16x32_bf16 v[54:57], v[150:153], v[178:181], v[54:57]
	v_mfma_f32_16x16x32_bf16 v[50:53], v[170:173], v[178:181], v[50:53]
	v_mfma_f32_16x16x32_bf16 v[34:37], v[150:153], v[190:193], v[34:37]
	v_mfma_f32_16x16x32_bf16 v[46:49], v[170:173], v[190:193], v[46:49]
	v_mfma_f32_16x16x32_bf16 v[30:33], v[150:153], v[198:201], v[30:33]
	v_mfma_f32_16x16x32_bf16 v[26:29], v[170:173], v[198:201], v[26:29]
	v_mfma_f32_16x16x32_bf16 v[14:17], v[150:153], v[206:209], v[14:17]
	v_mfma_f32_16x16x32_bf16 v[10:13], v[170:173], v[206:209], v[10:13]
	s_setprio 0
	s_barrier
	s_add_i32 s52, 0, 0x18000
	s_add_i32 s53, 0, 0x1c000
	v_add_u32_e32 v142, s52, v159
	v_add_u32_e32 v170, s53, v159
	ds_read_b128 v[130:133], v142
	ds_read_b128 v[134:137], v142 offset:1024
	ds_read_b128 v[138:141], v142 offset:2048
	ds_read_b128 v[142:145], v142 offset:3072
	ds_read_b128 v[146:149], v170
	ds_read_b128 v[150:153], v170 offset:1024
	ds_read_b128 v[154:157], v170 offset:2048
	ds_read_b128 v[170:173], v170 offset:3072
	s_add_u32 s14, s14, s86
	s_addc_u32 s15, s15, 0
	s_mov_b32 m0, s22
	ds_read_b128 v[174:177], v188 offset:32768
	ds_read_b128 v[178:181], v188 offset:33792
	ds_read_b128 v[182:185], v188 offset:34816
	ds_read_b128 v[190:193], v188 offset:35840
	ds_read_b128 v[194:197], v188 offset:36864
	ds_read_b128 v[198:201], v188 offset:37888
	ds_read_b128 v[202:205], v188 offset:38912
	ds_read_b128 v[206:209], v188 offset:39936
	global_load_lds_dwordx4 v162, s[14:15]
	s_mov_b32 m0, s23
	s_nop 0
	global_load_lds_dwordx4 v164, s[14:15]
	s_waitcnt vmcnt(8)
	s_waitcnt lgkmcnt(0)
	s_barrier
	s_setprio 1
	s_waitcnt lgkmcnt(0)
	v_mfma_f32_16x16x32_bf16 v[126:129], v[130:133], v[174:177], v[126:129]
	v_mfma_f32_16x16x32_bf16 v[122:125], v[138:141], v[174:177], v[122:125]
	v_mfma_f32_16x16x32_bf16 v[110:113], v[130:133], v[182:185], v[110:113]
	v_mfma_f32_16x16x32_bf16 v[106:109], v[138:141], v[182:185], v[106:109]
	v_mfma_f32_16x16x32_bf16 v[94:97], v[130:133], v[194:197], v[94:97]
	v_mfma_f32_16x16x32_bf16 v[90:93], v[138:141], v[194:197], v[90:93]
	v_mfma_f32_16x16x32_bf16 v[78:81], v[130:133], v[202:205], v[78:81]
	v_mfma_f32_16x16x32_bf16 v[74:77], v[138:141], v[202:205], v[74:77]
	v_mfma_f32_16x16x32_bf16 v[126:129], v[134:137], v[178:181], v[126:129]
	v_mfma_f32_16x16x32_bf16 v[122:125], v[142:145], v[178:181], v[122:125]
	v_mfma_f32_16x16x32_bf16 v[110:113], v[134:137], v[190:193], v[110:113]
	v_mfma_f32_16x16x32_bf16 v[106:109], v[142:145], v[190:193], v[106:109]
	v_mfma_f32_16x16x32_bf16 v[94:97], v[134:137], v[198:201], v[94:97]
	v_mfma_f32_16x16x32_bf16 v[90:93], v[142:145], v[198:201], v[90:93]
	v_mfma_f32_16x16x32_bf16 v[78:81], v[134:137], v[206:209], v[78:81]
	v_mfma_f32_16x16x32_bf16 v[74:77], v[142:145], v[206:209], v[74:77]
	s_setprio 0
	s_setprio 1
	v_mfma_f32_16x16x32_bf16 v[118:121], v[146:149], v[174:177], v[118:121]
	v_mfma_f32_16x16x32_bf16 v[114:117], v[154:157], v[174:177], v[114:117]
	v_mfma_f32_16x16x32_bf16 v[102:105], v[146:149], v[182:185], v[102:105]
	v_mfma_f32_16x16x32_bf16 v[98:101], v[154:157], v[182:185], v[98:101]
	v_mfma_f32_16x16x32_bf16 v[86:89], v[146:149], v[194:197], v[86:89]
	v_mfma_f32_16x16x32_bf16 v[82:85], v[154:157], v[194:197], v[82:85]
	v_mfma_f32_16x16x32_bf16 v[70:73], v[146:149], v[202:205], v[70:73]
	v_mfma_f32_16x16x32_bf16 v[66:69], v[154:157], v[202:205], v[66:69]
	v_mfma_f32_16x16x32_bf16 v[118:121], v[150:153], v[178:181], v[118:121]
	v_mfma_f32_16x16x32_bf16 v[114:117], v[170:173], v[178:181], v[114:117]
	v_mfma_f32_16x16x32_bf16 v[102:105], v[150:153], v[190:193], v[102:105]
	v_mfma_f32_16x16x32_bf16 v[98:101], v[170:173], v[190:193], v[98:101]
	v_mfma_f32_16x16x32_bf16 v[86:89], v[150:153], v[198:201], v[86:89]
	v_mfma_f32_16x16x32_bf16 v[82:85], v[170:173], v[198:201], v[82:85]
	v_mfma_f32_16x16x32_bf16 v[70:73], v[150:153], v[206:209], v[70:73]
	v_mfma_f32_16x16x32_bf16 v[66:69], v[170:173], v[206:209], v[66:69]
	s_setprio 0
	s_barrier
; #define PG8_STAGE(bufoff, gbase, voff) do { _Pragma("unroll") for (int _i = 0; _i < 2; ++_i) \
;         __builtin_amdgcn_global_load_lds((const unsigned*)((const char*)(gbase) + (voff)[_i]), (PG8_LAS unsigned*)(lds + (bufoff) + ldsw + _i * 8192), 16, 0, 0); } while (0)
; #define PG8_LDA(dst, b, h) do { _Pragma("unroll") for (int m = 0; m < 4; ++m) _Pragma("unroll") for (int k = 0; k < 2; ++k) dst[m][k] = *(const PG8_LAS bf16x8*)(lds + PG8_SA(b, h) + aoff + m * 2048 + k * 1024); } while (0)
; #define PG8_MMA(ai, bj, At, Bt) do { __builtin_amdgcn_s_setprio(1); _Pragma("unroll") for (int m = 0; m < 4; ++m) _Pragma("unroll") for (int n = 0; n < 2; ++n) _Pragma("unroll") for (int k = 0; k < 2; ++k) \
;         acc[ai][bj][m][n] = __builtin_amdgcn_mfma_f32_16x16x32_bf16(Bt[n][k], At[m][k], acc[ai][bj][m][n], 0, 0, 0); __builtin_amdgcn_s_setprio(0); } while (0)
; #define PG8_WAIT_V(n) asm volatile("s_waitcnt vmcnt(" #n ")" ::: "memory")
; #define PG8_WAIT_L(n) asm volatile("s_waitcnt lgkmcnt(" #n ")" ::: "memory")
; #define PG8_BAR __builtin_amdgcn_s_barrier()
; #define PG8_SCHED __builtin_amdgcn_sched_barrier(0)
; template <class Epi, class Sched, bool ALIGN_EPI = false, bool SP2 = false>
; __device__ __forceinline__ void gemm_phase(PG8_LAS unsigned char* lds, const Gemm g, const Sched& S, const Epi& E) {
;     ...
;             PG8_LDA(At, 1, 1); PG8_STAGE(PG8_SB(1, 0), b3, voffB); PG8_STAGE(PG8_SB(1, 1), b3 + hstep, voffB); PG8_STAGE(PG8_SA(1, 0), a3, voffA);
;             PG8_WAIT_V(8); PG8_WAIT_L(0); PG8_BAR; PG8_MMA(1, 0, At, B0); PG8_MMA(1, 1, At, B1); PG8_BAR; PG8_SCHED;
	s_add_i32 s14, s52, s19
	v_lshl_add_u64 v[210:211], v[210:211], 0, s[78:79]
	s_mov_b32 m0, s14
	ds_read_b128 v[174:177], v188 offset:49152
	ds_read_b128 v[178:181], v188 offset:50176
	ds_read_b128 v[182:185], v188 offset:51200
	ds_read_b128 v[190:193], v188 offset:52224
	ds_read_b128 v[194:197], v188 offset:53248
	ds_read_b128 v[198:201], v188 offset:54272
	ds_read_b128 v[202:205], v188 offset:55296
	ds_read_b128 v[206:209], v188 offset:56320
	global_load_lds_dwordx4 v[210:211], off
	v_lshl_add_u64 v[210:211], v[212:213], 0, s[78:79]
	s_add_i32 m0, s14, 0x2000
	s_add_i32 s14, s53, s19
	global_load_lds_dwordx4 v[210:211], off
	v_lshl_add_u64 v[210:211], v[218:219], 0, s[78:79]
	s_mov_b32 m0, s14
	s_nop 0
	global_load_lds_dwordx4 v[210:211], off
	v_lshl_add_u64 v[210:211], v[220:221], 0, s[78:79]
	s_add_i32 m0, s14, 0x2000
	s_nop 0
	global_load_lds_dwordx4 v[210:211], off
	v_lshl_add_u64 v[210:211], v[222:223], 0, s[78:79]
	s_mov_b32 m0, s24
	s_nop 0
	global_load_lds_dwordx4 v[210:211], off
	v_lshl_add_u64 v[210:211], v[224:225], 0, s[78:79]
	s_mov_b32 m0, s25
	s_nop 0
	global_load_lds_dwordx4 v[210:211], off
	s_waitcnt vmcnt(8)
	s_waitcnt lgkmcnt(0)
	s_barrier
	s_setprio 1
	s_waitcnt lgkmcnt(0)
	v_mfma_f32_16x16x32_bf16 v[62:65], v[130:133], v[174:177], v[62:65]
	v_mfma_f32_16x16x32_bf16 v[58:61], v[138:141], v[174:177], v[58:61]
	v_mfma_f32_16x16x32_bf16 v[42:45], v[130:133], v[182:185], v[42:45]
	v_mfma_f32_16x16x32_bf16 v[38:41], v[138:141], v[182:185], v[38:41]
	v_mfma_f32_16x16x32_bf16 v[22:25], v[130:133], v[194:197], v[22:25]
	v_mfma_f32_16x16x32_bf16 v[18:21], v[138:141], v[194:197], v[18:21]
	v_mfma_f32_16x16x32_bf16 v[6:9], v[130:133], v[202:205], v[6:9]
	v_mfma_f32_16x16x32_bf16 v[2:5], v[138:141], v[202:205], v[2:5]
	v_mfma_f32_16x16x32_bf16 v[62:65], v[134:137], v[178:181], v[62:65]
	v_mfma_f32_16x16x32_bf16 v[58:61], v[142:145], v[178:181], v[58:61]
	v_mfma_f32_16x16x32_bf16 v[42:45], v[134:137], v[190:193], v[42:45]
	v_mfma_f32_16x16x32_bf16 v[38:41], v[142:145], v[190:193], v[38:41]
	v_mfma_f32_16x16x32_bf16 v[22:25], v[134:137], v[198:201], v[22:25]
	v_mfma_f32_16x16x32_bf16 v[18:21], v[142:145], v[198:201], v[18:21]
	v_mfma_f32_16x16x32_bf16 v[6:9], v[134:137], v[206:209], v[6:9]
	v_mfma_f32_16x16x32_bf16 v[2:5], v[142:145], v[206:209], v[2:5]
	s_setprio 0
	s_setprio 1
	v_mfma_f32_16x16x32_bf16 v[54:57], v[146:149], v[174:177], v[54:57]
	v_mfma_f32_16x16x32_bf16 v[50:53], v[154:157], v[174:177], v[50:53]
	v_mfma_f32_16x16x32_bf16 v[34:37], v[146:149], v[182:185], v[34:37]
	v_mfma_f32_16x16x32_bf16 v[46:49], v[154:157], v[182:185], v[46:49]
	v_mfma_f32_16x16x32_bf16 v[30:33], v[146:149], v[194:197], v[30:33]
	v_mfma_f32_16x16x32_bf16 v[26:29], v[154:157], v[194:197], v[26:29]
	v_mfma_f32_16x16x32_bf16 v[14:17], v[146:149], v[202:205], v[14:17]
	v_mfma_f32_16x16x32_bf16 v[10:13], v[154:157], v[202:205], v[10:13]
	v_mfma_f32_16x16x32_bf16 v[54:57], v[150:153], v[178:181], v[54:57]
	v_mfma_f32_16x16x32_bf16 v[50:53], v[170:173], v[178:181], v[50:53]
	v_mfma_f32_16x16x32_bf16 v[34:37], v[150:153], v[190:193], v[34:37]
	v_mfma_f32_16x16x32_bf16 v[46:49], v[170:173], v[190:193], v[46:49]
	v_mfma_f32_16x16x32_bf16 v[30:33], v[150:153], v[198:201], v[30:33]
	v_mfma_f32_16x16x32_bf16 v[26:29], v[170:173], v[198:201], v[26:29]
	v_mfma_f32_16x16x32_bf16 v[14:17], v[150:153], v[206:209], v[14:17]
	v_mfma_f32_16x16x32_bf16 v[10:13], v[170:173], v[206:209], v[10:13]
	s_setprio 0
	s_barrier
	s_add_u32 s44, s44, 0x100
	s_addc_u32 s45, s45, 0
	s_add_u32 s12, s12, 0x100
	s_addc_u32 s13, s13, 0
	s_cmp_ge_u32 s51, s29
	s_mov_b32 s14, s51
	s_cbranch_scc0 .LBB0_458
	s_and_b64 vcc, exec, s[6:7]
	s_cbranch_vccz .LBB0_461
	s_barrier

; #define PG8_STAGE(bufoff, gbase, voff) do { _Pragma("unroll") for (int _i = 0; _i < 2; ++_i) \
;         __builtin_amdgcn_global_load_lds((const unsigned*)((const char*)(gbase) + (voff)[_i]), (PG8_LAS unsigned*)(lds + (bufoff) + ldsw + _i * 8192), 16, 0, 0); } while (0)
; #define PG8_LDA(dst, b, h) do { _Pragma("unroll") for (int m = 0; m < 4; ++m) _Pragma("unroll") for (int k = 0; k < 2; ++k) dst[m][k] = *(const PG8_LAS bf16x8*)(lds + PG8_SA(b, h) + aoff + m * 2048 + k * 1024); } while (0)
; #define PG8_LDB(dst, b, h) do { _Pragma("unroll") for (int n = 0; n < 2; ++n) _Pragma("unroll") for (int k = 0; k < 2; ++k) dst[n][k] = *(const PG8_LAS bf16x8*)(lds + PG8_SB(b, h) + boff + n * 2048 + k * 1024); } while (0)
; #define PG8_MMA(ai, bj, At, Bt) do { __builtin_amdgcn_s_setprio(1); _Pragma("unroll") for (int m = 0; m < 4; ++m) _Pragma("unroll") for (int n = 0; n < 2; ++n) _Pragma("unroll") for (int k = 0; k < 2; ++k) \
;         acc[ai][bj][m][n] = __builtin_amdgcn_mfma_f32_16x16x32_bf16(Bt[n][k], At[m][k], acc[ai][bj][m][n], 0, 0, 0); __builtin_amdgcn_s_setprio(0); } while (0)
; #define PG8_WAIT_V(n) asm volatile("s_waitcnt vmcnt(" #n ")" ::: "memory")
; #define PG8_WAIT_L(n) asm volatile("s_waitcnt lgkmcnt(" #n ")" ::: "memory")
; #define PG8_BAR __builtin_amdgcn_s_barrier()
; #define PG8_SCHED __builtin_amdgcn_sched_barrier(0)
; template <class Epi, class Sched, bool ALIGN_EPI = false, bool SP2 = false>
; __device__ __forceinline__ void gemm_phase(PG8_LAS unsigned char* lds, const Gemm g, const Sched& S, const Epi& E) {
;     ...
;             PG8_LDB(B0, 0, 0); PG8_LDB(B1, 0, 1); PG8_SCHED; PG8_LDA(At, 0, 0); PG8_STAGE(PG8_SA(1, 1), a1 + hstep, voffA);
;             PG8_WAIT_V(8); PG8_WAIT_L(0); PG8_BAR; PG8_MMA(0, 0, At, B0); PG8_MMA(0, 1, At, B1); PG8_BAR; PG8_SCHED;
;             PG8_LDA(At, 0, 1); PG8_STAGE(PG8_SB(0, 0), b2, voffB); PG8_STAGE(PG8_SB(0, 1), b2 + hstep, voffB); PG8_STAGE(PG8_SA(0, 0), a2, voffA);
.LBB0_571:
	s_add_u32 s16, s14, 0xfff80080
	s_addc_u32 s17, s15, -1
	s_add_i32 s48, 0, 0x10000
	s_cmp_eq_u32 s47, 28
	s_cselect_b32 s19, s9, s17
	s_cselect_b32 s18, s43, s16
	s_cselect_b32 s17, s7, s46
	s_cselect_b32 s16, s44, s45
	s_add_i32 s50, 0, 0x14000
	v_add_u32_e32 v156, s48, v140
	v_add_u32_e32 v172, s50, v140
	ds_read_b128 v[144:147], v156
	ds_read_b128 v[148:151], v156 offset:1024
	ds_read_b128 v[152:155], v156 offset:2048
	ds_read_b128 v[156:159], v156 offset:3072
	ds_read_b128 v[160:163], v172
	ds_read_b128 v[164:167], v172 offset:1024
	ds_read_b128 v[168:171], v172 offset:2048
	ds_read_b128 v[172:175], v172 offset:3072
	s_add_i32 m0, s23, 0xc000
	ds_read_b128 v[176:179], v143
	ds_read_b128 v[180:183], v143 offset:1024
	ds_read_b128 v[184:187], v143 offset:2048
	ds_read_b128 v[188:191], v143 offset:3072
	ds_read_b128 v[192:195], v143 offset:4096
	ds_read_b128 v[196:199], v143 offset:5120
	ds_read_b128 v[200:203], v143 offset:6144
	ds_read_b128 v[204:207], v143 offset:7168
	global_load_lds_dwordx4 v138, s[14:15]
	s_add_i32 m0, s23, 0xe000
	s_nop 0
	global_load_lds_dwordx4 v136, s[14:15]
	s_waitcnt vmcnt(8)
	s_waitcnt lgkmcnt(0)
	s_barrier
	s_setprio 1
	s_waitcnt lgkmcnt(0)
	v_mfma_f32_16x16x32_bf16 v[114:117], v[144:147], v[176:179], v[114:117]
	v_mfma_f32_16x16x32_bf16 v[118:121], v[152:155], v[176:179], v[118:121]
	v_mfma_f32_16x16x32_bf16 v[102:105], v[144:147], v[184:187], v[102:105]
	v_mfma_f32_16x16x32_bf16 v[106:109], v[152:155], v[184:187], v[106:109]
	v_mfma_f32_16x16x32_bf16 v[82:85], v[144:147], v[192:195], v[82:85]
	v_mfma_f32_16x16x32_bf16 v[86:89], v[152:155], v[192:195], v[86:89]
	v_mfma_f32_16x16x32_bf16 v[66:69], v[144:147], v[200:203], v[66:69]
	v_mfma_f32_16x16x32_bf16 v[70:73], v[152:155], v[200:203], v[70:73]
	v_mfma_f32_16x16x32_bf16 v[114:117], v[148:151], v[180:183], v[114:117]
	v_mfma_f32_16x16x32_bf16 v[118:121], v[156:159], v[180:183], v[118:121]
	v_mfma_f32_16x16x32_bf16 v[102:105], v[148:151], v[188:191], v[102:105]
	v_mfma_f32_16x16x32_bf16 v[106:109], v[156:159], v[188:191], v[106:109]
	v_mfma_f32_16x16x32_bf16 v[82:85], v[148:151], v[196:199], v[82:85]
	v_mfma_f32_16x16x32_bf16 v[86:89], v[156:159], v[196:199], v[86:89]
	v_mfma_f32_16x16x32_bf16 v[66:69], v[148:151], v[204:207], v[66:69]
	v_mfma_f32_16x16x32_bf16 v[70:73], v[156:159], v[204:207], v[70:73]
	s_setprio 0
	s_setprio 1
	v_mfma_f32_16x16x32_bf16 v[122:125], v[160:163], v[176:179], v[122:125]
	v_mfma_f32_16x16x32_bf16 v[126:129], v[168:171], v[176:179], v[126:129]
	v_mfma_f32_16x16x32_bf16 v[110:113], v[160:163], v[184:187], v[110:113]
	v_mfma_f32_16x16x32_bf16 v[98:101], v[168:171], v[184:187], v[98:101]
	v_mfma_f32_16x16x32_bf16 v[94:97], v[160:163], v[192:195], v[94:97]
	v_mfma_f32_16x16x32_bf16 v[90:93], v[168:171], v[192:195], v[90:93]
	v_mfma_f32_16x16x32_bf16 v[78:81], v[160:163], v[200:203], v[78:81]
	v_mfma_f32_16x16x32_bf16 v[74:77], v[168:171], v[200:203], v[74:77]
	v_mfma_f32_16x16x32_bf16 v[122:125], v[164:167], v[180:183], v[122:125]
	v_mfma_f32_16x16x32_bf16 v[126:129], v[172:175], v[180:183], v[126:129]
	v_mfma_f32_16x16x32_bf16 v[110:113], v[164:167], v[188:191], v[110:113]
	v_mfma_f32_16x16x32_bf16 v[98:101], v[172:175], v[188:191], v[98:101]
	v_mfma_f32_16x16x32_bf16 v[94:97], v[164:167], v[196:199], v[94:97]
	v_mfma_f32_16x16x32_bf16 v[90:93], v[172:175], v[196:199], v[90:93]
	v_mfma_f32_16x16x32_bf16 v[78:81], v[164:167], v[204:207], v[78:81]
	v_mfma_f32_16x16x32_bf16 v[74:77], v[172:175], v[204:207], v[74:77]
	s_setprio 0
	s_barrier
	s_add_i32 s48, s48, s22
	v_lshl_add_u64 v[208:209], s[16:17], 0, v[0:1]
	s_mov_b32 m0, s48
	ds_read_b128 v[176:179], v143 offset:16384
	ds_read_b128 v[180:183], v143 offset:17408
	ds_read_b128 v[184:187], v143 offset:18432
	ds_read_b128 v[188:191], v143 offset:19456
	ds_read_b128 v[192:195], v143 offset:20480
	ds_read_b128 v[196:199], v143 offset:21504
	ds_read_b128 v[200:203], v143 offset:22528
	ds_read_b128 v[204:207], v143 offset:23552
	global_load_lds_dwordx4 v0, s[16:17]
	s_add_i32 m0, s48, 0x2000
	s_add_u32 s48, s16, 0x80000
	v_lshl_add_u64 v[210:211], s[16:17], 0, v[130:131]
	s_addc_u32 s49, s17, 0
	s_add_i32 s50, s50, s22
	global_load_lds_dwordx4 v130, s[16:17]
	s_mov_b32 m0, s50
	v_lshl_add_u64 v[218:219], s[18:19], 0, v[132:133]
	global_load_lds_dwordx4 v0, s[48:49]
	s_add_i32 m0, s50, 0x2000
	s_nop 0
	global_load_lds_dwordx4 v130, s[48:49]
	v_lshl_add_u64 v[212:213], s[18:19], 0, v[134:135]
	s_mov_b32 m0, s23
	s_nop 0
	global_load_lds_dwordx4 v134, s[18:19]
	s_mov_b32 m0, s24
	s_nop 0
	global_load_lds_dwordx4 v132, s[18:19]
	s_waitcnt vmcnt(8)
	s_waitcnt lgkmcnt(0)
	s_barrier
; #define PG8_STAGE(bufoff, gbase, voff) do { _Pragma("unroll") for (int _i = 0; _i < 2; ++_i) \
;         __builtin_amdgcn_global_load_lds((const unsigned*)((const char*)(gbase) + (voff)[_i]), (PG8_LAS unsigned*)(lds + (bufoff) + ldsw + _i * 8192), 16, 0, 0); } while (0)
; #define PG8_LDA(dst, b, h) do { _Pragma("unroll") for (int m = 0; m < 4; ++m) _Pragma("unroll") for (int k = 0; k < 2; ++k) dst[m][k] = *(const PG8_LAS bf16x8*)(lds + PG8_SA(b, h) + aoff + m * 2048 + k * 1024); } while (0)
; #define PG8_LDB(dst, b, h) do { _Pragma("unroll") for (int n = 0; n < 2; ++n) _Pragma("unroll") for (int k = 0; k < 2; ++k) dst[n][k] = *(const PG8_LAS bf16x8*)(lds + PG8_SB(b, h) + boff + n * 2048 + k * 1024); } while (0)
; #define PG8_MMA(ai, bj, At, Bt) do { __builtin_amdgcn_s_setprio(1); _Pragma("unroll") for (int m = 0; m < 4; ++m) _Pragma("unroll") for (int n = 0; n < 2; ++n) _Pragma("unroll") for (int k = 0; k < 2; ++k) \
;         acc[ai][bj][m][n] = __builtin_amdgcn_mfma_f32_16x16x32_bf16(Bt[n][k], At[m][k], acc[ai][bj][m][n], 0, 0, 0); __builtin_amdgcn_s_setprio(0); } while (0)
; #define PG8_WAIT_V(n) asm volatile("s_waitcnt vmcnt(" #n ")" ::: "memory")
; #define PG8_WAIT_L(n) asm volatile("s_waitcnt lgkmcnt(" #n ")" ::: "memory")
; #define PG8_BAR __builtin_amdgcn_s_barrier()
; #define PG8_SCHED __builtin_amdgcn_sched_barrier(0)
; template <class Epi, class Sched, bool ALIGN_EPI = false, bool SP2 = false>
; __device__ __forceinline__ void gemm_phase(PG8_LAS unsigned char* lds, const Gemm g, const Sched& S, const Epi& E) {
;     ...
;             PG8_WAIT_V(8); PG8_WAIT_L(0); PG8_BAR; PG8_MMA(1, 0, At, B0); PG8_MMA(1, 1, At, B1); PG8_BAR; PG8_SCHED;
;             PG8_LDB(B0, 1, 0); PG8_LDB(B1, 1, 1); PG8_SCHED; PG8_LDA(At, 1, 0); PG8_STAGE(PG8_SA(0, 1), a2 + hstep, voffA);
;             PG8_WAIT_V(8); PG8_WAIT_L(0); PG8_BAR; PG8_MMA(0, 0, At, B0); PG8_MMA(0, 1, At, B1); PG8_BAR; PG8_SCHED;
	s_setprio 1
	s_waitcnt lgkmcnt(0)
	v_mfma_f32_16x16x32_bf16 v[50:53], v[144:147], v[176:179], v[50:53]
	v_mfma_f32_16x16x32_bf16 v[54:57], v[152:155], v[176:179], v[54:57]
	v_mfma_f32_16x16x32_bf16 v[34:37], v[144:147], v[184:187], v[34:37]
	v_mfma_f32_16x16x32_bf16 v[38:41], v[152:155], v[184:187], v[38:41]
	v_mfma_f32_16x16x32_bf16 v[18:21], v[144:147], v[192:195], v[18:21]
	v_mfma_f32_16x16x32_bf16 v[22:25], v[152:155], v[192:195], v[22:25]
	v_mfma_f32_16x16x32_bf16 v[2:5], v[144:147], v[200:203], v[2:5]
	v_mfma_f32_16x16x32_bf16 v[6:9], v[152:155], v[200:203], v[6:9]
	v_mfma_f32_16x16x32_bf16 v[50:53], v[148:151], v[180:183], v[50:53]
	v_mfma_f32_16x16x32_bf16 v[54:57], v[156:159], v[180:183], v[54:57]
	v_mfma_f32_16x16x32_bf16 v[34:37], v[148:151], v[188:191], v[34:37]
	v_mfma_f32_16x16x32_bf16 v[38:41], v[156:159], v[188:191], v[38:41]
	v_mfma_f32_16x16x32_bf16 v[18:21], v[148:151], v[196:199], v[18:21]
	v_mfma_f32_16x16x32_bf16 v[22:25], v[156:159], v[196:199], v[22:25]
	v_mfma_f32_16x16x32_bf16 v[2:5], v[148:151], v[204:207], v[2:5]
	v_mfma_f32_16x16x32_bf16 v[6:9], v[156:159], v[204:207], v[6:9]
	s_setprio 0
	s_setprio 1
	v_mfma_f32_16x16x32_bf16 v[62:65], v[160:163], v[176:179], v[62:65]
	v_mfma_f32_16x16x32_bf16 v[58:61], v[168:171], v[176:179], v[58:61]
	v_mfma_f32_16x16x32_bf16 v[42:45], v[160:163], v[184:187], v[42:45]
	v_mfma_f32_16x16x32_bf16 v[46:49], v[168:171], v[184:187], v[46:49]
	v_mfma_f32_16x16x32_bf16 v[30:33], v[160:163], v[192:195], v[30:33]
	v_mfma_f32_16x16x32_bf16 v[26:29], v[168:171], v[192:195], v[26:29]
	v_mfma_f32_16x16x32_bf16 v[14:17], v[160:163], v[200:203], v[14:17]
	v_mfma_f32_16x16x32_bf16 v[10:13], v[168:171], v[200:203], v[10:13]
	v_mfma_f32_16x16x32_bf16 v[62:65], v[164:167], v[180:183], v[62:65]
	v_mfma_f32_16x16x32_bf16 v[58:61], v[172:175], v[180:183], v[58:61]
	v_mfma_f32_16x16x32_bf16 v[42:45], v[164:167], v[188:191], v[42:45]
	v_mfma_f32_16x16x32_bf16 v[46:49], v[172:175], v[188:191], v[46:49]
	v_mfma_f32_16x16x32_bf16 v[30:33], v[164:167], v[196:199], v[30:33]
	v_mfma_f32_16x16x32_bf16 v[26:29], v[172:175], v[196:199], v[26:29]
	v_mfma_f32_16x16x32_bf16 v[14:17], v[164:167], v[204:207], v[14:17]
	v_mfma_f32_16x16x32_bf16 v[10:13], v[172:175], v[204:207], v[10:13]
	s_setprio 0
	s_barrier
	s_add_i32 s48, 0, 0x18000
	s_add_i32 s49, 0, 0x1c000
	v_add_u32_e32 v156, s48, v140
	v_add_u32_e32 v172, s49, v140
	ds_read_b128 v[144:147], v156
	ds_read_b128 v[148:151], v156 offset:1024
	ds_read_b128 v[152:155], v156 offset:2048
	ds_read_b128 v[156:159], v156 offset:3072
	ds_read_b128 v[160:163], v172
	ds_read_b128 v[164:167], v172 offset:1024
	ds_read_b128 v[168:171], v172 offset:2048
	ds_read_b128 v[172:175], v172 offset:3072
	s_add_u32 s18, s18, 0x80000
	s_addc_u32 s19, s19, 0
	s_mov_b32 m0, s25
	ds_read_b128 v[176:179], v143 offset:32768
	ds_read_b128 v[180:183], v143 offset:33792
	ds_read_b128 v[184:187], v143 offset:34816
	ds_read_b128 v[188:191], v143 offset:35840
	ds_read_b128 v[192:195], v143 offset:36864
	ds_read_b128 v[196:199], v143 offset:37888
	ds_read_b128 v[200:203], v143 offset:38912
	ds_read_b128 v[204:207], v143 offset:39936
	global_load_lds_dwordx4 v134, s[18:19]
	s_mov_b32 m0, s26
	s_nop 0
	global_load_lds_dwordx4 v132, s[18:19]
	s_waitcnt vmcnt(8)
	s_waitcnt lgkmcnt(0)
	s_barrier
	s_setprio 1
	s_waitcnt lgkmcnt(0)
	v_mfma_f32_16x16x32_bf16 v[114:117], v[144:147], v[176:179], v[114:117]
	v_mfma_f32_16x16x32_bf16 v[118:121], v[152:155], v[176:179], v[118:121]
	v_mfma_f32_16x16x32_bf16 v[102:105], v[144:147], v[184:187], v[102:105]
	v_mfma_f32_16x16x32_bf16 v[106:109], v[152:155], v[184:187], v[106:109]
	v_mfma_f32_16x16x32_bf16 v[82:85], v[144:147], v[192:195], v[82:85]
	v_mfma_f32_16x16x32_bf16 v[86:89], v[152:155], v[192:195], v[86:89]
	v_mfma_f32_16x16x32_bf16 v[66:69], v[144:147], v[200:203], v[66:69]
	v_mfma_f32_16x16x32_bf16 v[70:73], v[152:155], v[200:203], v[70:73]
	v_mfma_f32_16x16x32_bf16 v[114:117], v[148:151], v[180:183], v[114:117]
	v_mfma_f32_16x16x32_bf16 v[118:121], v[156:159], v[180:183], v[118:121]
	v_mfma_f32_16x16x32_bf16 v[102:105], v[148:151], v[188:191], v[102:105]
	v_mfma_f32_16x16x32_bf16 v[106:109], v[156:159], v[188:191], v[106:109]
	v_mfma_f32_16x16x32_bf16 v[82:85], v[148:151], v[196:199], v[82:85]
	v_mfma_f32_16x16x32_bf16 v[86:89], v[156:159], v[196:199], v[86:89]
	v_mfma_f32_16x16x32_bf16 v[66:69], v[148:151], v[204:207], v[66:69]
	v_mfma_f32_16x16x32_bf16 v[70:73], v[156:159], v[204:207], v[70:73]
	s_setprio 0
	s_setprio 1
	v_mfma_f32_16x16x32_bf16 v[122:125], v[160:163], v[176:179], v[122:125]
	v_mfma_f32_16x16x32_bf16 v[126:129], v[168:171], v[176:179], v[126:129]
	v_mfma_f32_16x16x32_bf16 v[110:113], v[160:163], v[184:187], v[110:113]
	v_mfma_f32_16x16x32_bf16 v[98:101], v[168:171], v[184:187], v[98:101]
	v_mfma_f32_16x16x32_bf16 v[94:97], v[160:163], v[192:195], v[94:97]
	v_mfma_f32_16x16x32_bf16 v[90:93], v[168:171], v[192:195], v[90:93]
	v_mfma_f32_16x16x32_bf16 v[78:81], v[160:163], v[200:203], v[78:81]
	v_mfma_f32_16x16x32_bf16 v[74:77], v[168:171], v[200:203], v[74:77]
	v_mfma_f32_16x16x32_bf16 v[122:125], v[164:167], v[180:183], v[122:125]
	v_mfma_f32_16x16x32_bf16 v[126:129], v[172:175], v[180:183], v[126:129]
	v_mfma_f32_16x16x32_bf16 v[110:113], v[164:167], v[188:191], v[110:113]
	v_mfma_f32_16x16x32_bf16 v[98:101], v[172:175], v[188:191], v[98:101]
	v_mfma_f32_16x16x32_bf16 v[94:97], v[164:167], v[196:199], v[94:97]
	v_mfma_f32_16x16x32_bf16 v[90:93], v[172:175], v[196:199], v[90:93]
	v_mfma_f32_16x16x32_bf16 v[78:81], v[164:167], v[204:207], v[78:81]
	v_mfma_f32_16x16x32_bf16 v[74:77], v[172:175], v[204:207], v[74:77]
	s_setprio 0
	s_barrier
; #define PG8_STAGE(bufoff, gbase, voff) do { _Pragma("unroll") for (int _i = 0; _i < 2; ++_i) \
;         __builtin_amdgcn_global_load_lds((const unsigned*)((const char*)(gbase) + (voff)[_i]), (PG8_LAS unsigned*)(lds + (bufoff) + ldsw + _i * 8192), 16, 0, 0); } while (0)
; #define PG8_LDA(dst, b, h) do { _Pragma("unroll") for (int m = 0; m < 4; ++m) _Pragma("unroll") for (int k = 0; k < 2; ++k) dst[m][k] = *(const PG8_LAS bf16x8*)(lds + PG8_SA(b, h) + aoff + m * 2048 + k * 1024); } while (0)
; #define PG8_MMA(ai, bj, At, Bt) do { __builtin_amdgcn_s_setprio(1); _Pragma("unroll") for (int m = 0; m < 4; ++m) _Pragma("unroll") for (int n = 0; n < 2; ++n) _Pragma("unroll") for (int k = 0; k < 2; ++k) \
;         acc[ai][bj][m][n] = __builtin_amdgcn_mfma_f32_16x16x32_bf16(Bt[n][k], At[m][k], acc[ai][bj][m][n], 0, 0, 0); __builtin_amdgcn_s_setprio(0); } while (0)
; #define PG8_WAIT_V(n) asm volatile("s_waitcnt vmcnt(" #n ")" ::: "memory")
; #define PG8_WAIT_L(n) asm volatile("s_waitcnt lgkmcnt(" #n ")" ::: "memory")
; #define PG8_BAR __builtin_amdgcn_s_barrier()
; #define PG8_SCHED __builtin_amdgcn_sched_barrier(0)
; template <class Epi, class Sched, bool ALIGN_EPI = false, bool SP2 = false>
; __device__ __forceinline__ void gemm_phase(PG8_LAS unsigned char* lds, const Gemm g, const Sched& S, const Epi& E) {
;     ...
;             PG8_LDA(At, 1, 1); PG8_STAGE(PG8_SB(1, 0), b3, voffB); PG8_STAGE(PG8_SB(1, 1), b3 + hstep, voffB); PG8_STAGE(PG8_SA(1, 0), a3, voffA);
;             PG8_WAIT_V(8); PG8_WAIT_L(0); PG8_BAR; PG8_MMA(1, 0, At, B0); PG8_MMA(1, 1, At, B1); PG8_BAR; PG8_SCHED;
	s_add_i32 s18, s48, s22
	v_lshl_add_u64 v[208:209], v[208:209], 0, s[78:79]
	s_mov_b32 m0, s18
	ds_read_b128 v[176:179], v143 offset:49152
	ds_read_b128 v[180:183], v143 offset:50176
	ds_read_b128 v[184:187], v143 offset:51200
	ds_read_b128 v[188:191], v143 offset:52224
	ds_read_b128 v[192:195], v143 offset:53248
	ds_read_b128 v[196:199], v143 offset:54272
	ds_read_b128 v[200:203], v143 offset:55296
	ds_read_b128 v[204:207], v143 offset:56320
	global_load_lds_dwordx4 v[208:209], off
	s_add_i32 m0, s18, 0x2000
	s_add_u32 s16, s16, 0x80080
	v_lshl_add_u64 v[208:209], v[210:211], 0, s[78:79]
	s_addc_u32 s17, s17, 0
	s_add_i32 s18, s49, s22
	global_load_lds_dwordx4 v[208:209], off
	s_mov_b32 m0, s18
	s_nop 0
	global_load_lds_dwordx4 v0, s[16:17]
	s_add_i32 m0, s18, 0x2000
	s_nop 0
	global_load_lds_dwordx4 v130, s[16:17]
	v_lshl_add_u64 v[208:209], v[212:213], 0, s[78:79]
	s_mov_b32 m0, s27
	s_nop 0
	global_load_lds_dwordx4 v[208:209], off
	v_lshl_add_u64 v[208:209], v[218:219], 0, s[78:79]
	s_mov_b32 m0, s28
	s_nop 0
	global_load_lds_dwordx4 v[208:209], off
	s_waitcnt vmcnt(8)
	s_waitcnt lgkmcnt(0)
	s_barrier
	s_setprio 1
	s_waitcnt lgkmcnt(0)
	v_mfma_f32_16x16x32_bf16 v[50:53], v[144:147], v[176:179], v[50:53]
	v_mfma_f32_16x16x32_bf16 v[54:57], v[152:155], v[176:179], v[54:57]
	v_mfma_f32_16x16x32_bf16 v[34:37], v[144:147], v[184:187], v[34:37]
	v_mfma_f32_16x16x32_bf16 v[38:41], v[152:155], v[184:187], v[38:41]
	v_mfma_f32_16x16x32_bf16 v[18:21], v[144:147], v[192:195], v[18:21]
	v_mfma_f32_16x16x32_bf16 v[22:25], v[152:155], v[192:195], v[22:25]
	v_mfma_f32_16x16x32_bf16 v[2:5], v[144:147], v[200:203], v[2:5]
	v_mfma_f32_16x16x32_bf16 v[6:9], v[152:155], v[200:203], v[6:9]
	v_mfma_f32_16x16x32_bf16 v[50:53], v[148:151], v[180:183], v[50:53]
	v_mfma_f32_16x16x32_bf16 v[54:57], v[156:159], v[180:183], v[54:57]
	v_mfma_f32_16x16x32_bf16 v[34:37], v[148:151], v[188:191], v[34:37]
	v_mfma_f32_16x16x32_bf16 v[38:41], v[156:159], v[188:191], v[38:41]
	v_mfma_f32_16x16x32_bf16 v[18:21], v[148:151], v[196:199], v[18:21]
	v_mfma_f32_16x16x32_bf16 v[22:25], v[156:159], v[196:199], v[22:25]
	v_mfma_f32_16x16x32_bf16 v[2:5], v[148:151], v[204:207], v[2:5]
	v_mfma_f32_16x16x32_bf16 v[6:9], v[156:159], v[204:207], v[6:9]
	s_setprio 0
	s_setprio 1
	v_mfma_f32_16x16x32_bf16 v[62:65], v[160:163], v[176:179], v[62:65]
	v_mfma_f32_16x16x32_bf16 v[58:61], v[168:171], v[176:179], v[58:61]
	v_mfma_f32_16x16x32_bf16 v[42:45], v[160:163], v[184:187], v[42:45]
	v_mfma_f32_16x16x32_bf16 v[46:49], v[168:171], v[184:187], v[46:49]
	v_mfma_f32_16x16x32_bf16 v[30:33], v[160:163], v[192:195], v[30:33]
	v_mfma_f32_16x16x32_bf16 v[26:29], v[168:171], v[192:195], v[26:29]
	v_mfma_f32_16x16x32_bf16 v[14:17], v[160:163], v[200:203], v[14:17]
	v_mfma_f32_16x16x32_bf16 v[10:13], v[168:171], v[200:203], v[10:13]
	v_mfma_f32_16x16x32_bf16 v[62:65], v[164:167], v[180:183], v[62:65]
	v_mfma_f32_16x16x32_bf16 v[58:61], v[172:175], v[180:183], v[58:61]
	v_mfma_f32_16x16x32_bf16 v[42:45], v[164:167], v[188:191], v[42:45]
	v_mfma_f32_16x16x32_bf16 v[46:49], v[172:175], v[188:191], v[46:49]
	v_mfma_f32_16x16x32_bf16 v[30:33], v[164:167], v[196:199], v[30:33]
	v_mfma_f32_16x16x32_bf16 v[26:29], v[172:175], v[196:199], v[26:29]
	v_mfma_f32_16x16x32_bf16 v[14:17], v[164:167], v[204:207], v[14:17]
	v_mfma_f32_16x16x32_bf16 v[10:13], v[172:175], v[204:207], v[10:13]
	s_setprio 0
	s_barrier
	s_add_i32 s47, s47, 2
	s_add_u32 s45, s45, 0x100
	s_addc_u32 s46, s46, 0
	s_add_u32 s14, s14, 0x100
	s_addc_u32 s15, s15, 0
	s_cmp_gt_u32 s47, 29
	s_cbranch_scc0 .LBB0_571
	s_and_b64 vcc, exec, s[4:5]
	v_readlane_b32 s47, v254, 33
	s_cbranch_vccz .LBB0_574
	s_barrier
